# grid-barrier poll backoff s_sleep 6 -> s_sleep 14 on top of v034
# baseline (speedup 1.0000x reference)
; __global__ void __launch_bounds__(512, 2) fwd_megakernel(Params p) {
;     ...
;   grid.sync();
.LBB0_135:
	s_sleep 14
	global_load_dword v2, v0, s[6:7] offset:32 sc1
	s_waitcnt vmcnt(0)
	v_and_b32_e32 v2, 0xffff0000, v2
	v_cmp_ne_u32_e32 vcc, v2, v1
	s_or_b64 s[8:9], vcc, s[8:9]
	s_andn2_b64 exec, exec, s[8:9]
	s_cbranch_execnz .LBB0_135

; __device__ __forceinline__ unsigned xb_ld(unsigned* p)              { return __hip_atomic_load(p, __ATOMIC_RELAXED, __HIP_MEMORY_SCOPE_AGENT); }
; __device__ __forceinline__ void xcd_barrier_complete(unsigned* bar, unsigned x, unsigned& nloc, unsigned& nx) {
;     ...
;   for (;;) {
;     sum = 0u; cnt = 0u; mine = 0u;
; #pragma unroll
;     for (unsigned j = 0; j < 16; ++j) { const unsigned c = xb_ld(&bar[XB_XCNT(j)]); sum += c; cnt += (c > 0u) ? 1u : 0u; mine = (j == x) ? c : mine; }
;     if (sum == G) break;
;     __builtin_amdgcn_s_sleep(1);
;     if ((++sp & 255u) == 0u) { if (xb_ld(&bar[XB_TMO])) break; if (sp > XB_SPIN_CAP) { atomicAdd(&bar[XB_TMO], 1u); break; } }
;   }
.LBB0_144:
	global_load_dword v15, v16, s[8:9] sc1
	global_load_dword v0, v16, s[10:11] sc1
	global_load_dword v1, v16, s[12:13] sc1
	global_load_dword v2, v16, s[14:15] sc1
	global_load_dword v3, v16, s[16:17] sc1
	global_load_dword v4, v16, s[18:19] sc1
	global_load_dword v5, v16, s[20:21] sc1
	global_load_dword v6, v16, s[22:23] sc1
	global_load_dword v7, v16, s[24:25] sc1
	global_load_dword v8, v16, s[26:27] sc1
	global_load_dword v9, v16, s[28:29] sc1
	global_load_dword v10, v16, s[30:31] sc1
	global_load_dword v11, v16, s[34:35] sc1
	global_load_dword v12, v16, s[36:37] sc1
	global_load_dword v13, v16, s[38:39] sc1
	global_load_dword v14, v16, s[40:41] sc1
	s_mov_b64 s[42:43], -1
	s_mov_b64 s[44:45], -1
	s_waitcnt vmcnt(14)
	v_add_u32_e32 v17, v0, v15
	s_waitcnt vmcnt(13)
	v_add_u32_e32 v17, v17, v1
	s_waitcnt vmcnt(12)
	v_add_u32_e32 v17, v17, v2
	s_waitcnt vmcnt(11)
	v_add_u32_e32 v17, v17, v3
	s_waitcnt vmcnt(10)
	v_add_u32_e32 v17, v17, v4
	s_waitcnt vmcnt(9)
	v_add_u32_e32 v17, v17, v5
	s_waitcnt vmcnt(8)
	v_add_u32_e32 v17, v17, v6
	s_waitcnt vmcnt(7)
	v_add_u32_e32 v17, v17, v7
	s_waitcnt vmcnt(6)
	v_add_u32_e32 v17, v17, v8
	s_waitcnt vmcnt(5)
	v_add_u32_e32 v17, v17, v9
	s_waitcnt vmcnt(4)
	v_add_u32_e32 v17, v17, v10
	s_waitcnt vmcnt(3)
	v_add_u32_e32 v17, v17, v11
	s_waitcnt vmcnt(2)
	v_add_u32_e32 v17, v17, v12
	s_waitcnt vmcnt(1)
	v_add_u32_e32 v17, v17, v13
	s_waitcnt vmcnt(0)
	v_add_u32_e32 v17, v17, v14
	v_cmp_eq_u32_e32 vcc, s0, v17
	s_cbranch_vccnz .LBB0_143
	s_and_b32 s2, s1, 0xff
	s_cmp_eq_u32 s2, 0
	s_mov_b64 s[46:47], -1
	s_sleep 14
	s_cbranch_scc0 .LBB0_148
	global_load_dword v17, v16, s[6:7] sc1
	s_waitcnt vmcnt(0)
	v_cmp_eq_u32_e32 vcc, 0, v17
	s_cbranch_vccnz .LBB0_150
	s_mov_b64 s[46:47], 0

; __device__ __forceinline__ unsigned xb_ld(unsigned* p)              { return __hip_atomic_load(p, __ATOMIC_RELAXED, __HIP_MEMORY_SCOPE_AGENT); }
; __device__ __forceinline__ unsigned xb_add(unsigned* p, unsigned v) { return __hip_atomic_fetch_add(p, v, __ATOMIC_RELAXED, __HIP_MEMORY_SCOPE_AGENT); }
; #define XB_SPIN(cond, bar) do { unsigned _sp = 0; while (cond) { __builtin_amdgcn_s_sleep(1); \
;     if ((++_sp & 255u) == 0u) { if (xb_ld(&(bar)[XB_TMO])) break; if (_sp > XB_SPIN_CAP) { atomicAdd(&(bar)[XB_TMO], 1u); break; } } } } while (0)
; __device__ __forceinline__ void xcd_barrier(const XcdBarrier& b) {
;     ...
;       else XB_SPIN(xb_ld(&bar[XB_TOPGEN]) == tg, bar);
;       __builtin_amdgcn_fence(__ATOMIC_ACQUIRE, "agent");
;       xb_add(&bar[XB_XGEN(b.x)], 1u);
;       asm volatile("s_waitcnt vmcnt(0)" ::: "memory");
;     } else {
;       XB_SPIN(xb_ld(&bar[XB_XGEN(b.x)]) == gen, bar);
.LBB0_162:
	s_and_b32 s1, s0, 0xff
	s_mov_b64 s[20:21], -1
	s_cmp_lg_u32 s1, 0
	s_mov_b64 s[24:25], -1
	s_sleep 14
	s_cbranch_scc1 .LBB0_165
	global_load_dword v2, v0, s[12:13] sc1
	s_waitcnt vmcnt(0)
	v_cmp_eq_u32_e32 vcc, 0, v2
	s_cbranch_vccnz .LBB0_167
	s_mov_b64 s[24:25], 0
	s_mov_b64 s[22:23], -1

; __device__ __forceinline__ unsigned xb_ld(unsigned* p)              { return __hip_atomic_load(p, __ATOMIC_RELAXED, __HIP_MEMORY_SCOPE_AGENT); }
; __device__ __forceinline__ unsigned xb_add(unsigned* p, unsigned v) { return __hip_atomic_fetch_add(p, v, __ATOMIC_RELAXED, __HIP_MEMORY_SCOPE_AGENT); }
; #define XB_SPIN(cond, bar) do { unsigned _sp = 0; while (cond) { __builtin_amdgcn_s_sleep(1); \
;     if ((++_sp & 255u) == 0u) { if (xb_ld(&(bar)[XB_TMO])) break; if (_sp > XB_SPIN_CAP) { atomicAdd(&(bar)[XB_TMO], 1u); break; } } } } while (0)
; __device__ __forceinline__ void xcd_barrier(const XcdBarrier& b) {
;     ...
;       else XB_SPIN(xb_ld(&bar[XB_TOPGEN]) == tg, bar);
;       __builtin_amdgcn_fence(__ATOMIC_ACQUIRE, "agent");
;       xb_add(&bar[XB_XGEN(b.x)], 1u);
;       asm volatile("s_waitcnt vmcnt(0)" ::: "memory");
;     } else {
;       XB_SPIN(xb_ld(&bar[XB_XGEN(b.x)]) == gen, bar);
.LBB0_179:
	s_and_b32 s1, s0, 0xff
	s_cmp_lg_u32 s1, 0
	s_mov_b64 s[22:23], -1
	s_sleep 14
	s_cbranch_scc1 .LBB0_182
	global_load_dword v1, v0, s[12:13] sc1
	s_waitcnt vmcnt(0)
	v_cmp_eq_u32_e32 vcc, 0, v1
	s_cbranch_vccnz .LBB0_184
	s_mov_b64 s[22:23], 0
	s_mov_b64 s[20:21], -1

; __device__ __forceinline__ unsigned xb_ld(unsigned* p)              { return __hip_atomic_load(p, __ATOMIC_RELAXED, __HIP_MEMORY_SCOPE_AGENT); }
; __device__ __forceinline__ void xcd_barrier_complete(unsigned* bar, unsigned x, unsigned& nloc, unsigned& nx) {
;     ...
;   for (;;) {
;     sum = 0u; cnt = 0u; mine = 0u;
; #pragma unroll
;     for (unsigned j = 0; j < 16; ++j) { const unsigned c = xb_ld(&bar[XB_XCNT(j)]); sum += c; cnt += (c > 0u) ? 1u : 0u; mine = (j == x) ? c : mine; }
;     if (sum == G) break;
;     __builtin_amdgcn_s_sleep(1);
;     if ((++sp & 255u) == 0u) { if (xb_ld(&bar[XB_TMO])) break; if (sp > XB_SPIN_CAP) { atomicAdd(&bar[XB_TMO], 1u); break; } }
;   }
.LBB0_552:
	global_load_dword v15, v16, s[8:9] sc1
	s_waitcnt lgkmcnt(0)
	global_load_dword v0, v16, s[10:11] sc1
	global_load_dword v1, v16, s[12:13] sc1
	global_load_dword v2, v16, s[14:15] sc1
	global_load_dword v3, v16, s[16:17] sc1
	global_load_dword v4, v16, s[18:19] sc1
	global_load_dword v5, v16, s[20:21] sc1
	global_load_dword v6, v16, s[22:23] sc1
	global_load_dword v7, v16, s[24:25] sc1
	global_load_dword v8, v16, s[26:27] sc1
	global_load_dword v9, v16, s[28:29] sc1
	global_load_dword v10, v16, s[30:31] sc1
	global_load_dword v11, v16, s[34:35] sc1
	global_load_dword v12, v16, s[36:37] sc1
	global_load_dword v13, v16, s[38:39] sc1
	global_load_dword v14, v16, s[40:41] sc1
	s_mov_b64 s[42:43], -1
	s_mov_b64 s[44:45], -1
	s_waitcnt vmcnt(14)
	v_add_u32_e32 v17, v0, v15
	s_waitcnt vmcnt(13)
	v_add_u32_e32 v17, v17, v1
	s_waitcnt vmcnt(12)
	v_add_u32_e32 v17, v17, v2
	s_waitcnt vmcnt(11)
	v_add_u32_e32 v17, v17, v3
	s_waitcnt vmcnt(10)
	v_add_u32_e32 v17, v17, v4
	s_waitcnt vmcnt(9)
	v_add_u32_e32 v17, v17, v5
	s_waitcnt vmcnt(8)
	v_add_u32_e32 v17, v17, v6
	s_waitcnt vmcnt(7)
	v_add_u32_e32 v17, v17, v7
	s_waitcnt vmcnt(6)
	v_add_u32_e32 v17, v17, v8
	s_waitcnt vmcnt(5)
	v_add_u32_e32 v17, v17, v9
	s_waitcnt vmcnt(4)
	v_add_u32_e32 v17, v17, v10
	s_waitcnt vmcnt(3)
	v_add_u32_e32 v17, v17, v11
	s_waitcnt vmcnt(2)
	v_add_u32_e32 v17, v17, v12
	s_waitcnt vmcnt(1)
	v_add_u32_e32 v17, v17, v13
	s_waitcnt vmcnt(0)
	v_add_u32_e32 v17, v17, v14
	v_cmp_eq_u32_e32 vcc, s0, v17
	s_cbranch_vccnz .LBB0_551
	s_and_b32 s2, s1, 0xff
	s_cmp_eq_u32 s2, 0
	s_mov_b64 s[46:47], -1
	s_sleep 14
	s_cbranch_scc0 .LBB0_556
	global_load_dword v17, v16, s[6:7] sc1
	s_waitcnt vmcnt(0)
	v_cmp_eq_u32_e32 vcc, 0, v17
	s_cbranch_vccnz .LBB0_558
	s_mov_b64 s[46:47], 0

; __device__ __forceinline__ unsigned xb_ld(unsigned* p)              { return __hip_atomic_load(p, __ATOMIC_RELAXED, __HIP_MEMORY_SCOPE_AGENT); }
; __device__ __forceinline__ void xcd_barrier_complete(unsigned* bar, unsigned x, unsigned& nloc, unsigned& nx) {
;     ...
;   for (;;) {
;     sum = 0u; cnt = 0u; mine = 0u;
; #pragma unroll
;     for (unsigned j = 0; j < 16; ++j) { const unsigned c = xb_ld(&bar[XB_XCNT(j)]); sum += c; cnt += (c > 0u) ? 1u : 0u; mine = (j == x) ? c : mine; }
;     if (sum == G) break;
;     __builtin_amdgcn_s_sleep(1);
;     if ((++sp & 255u) == 0u) { if (xb_ld(&bar[XB_TMO])) break; if (sp > XB_SPIN_CAP) { atomicAdd(&bar[XB_TMO], 1u); break; } }
;   }
.LBB0_679:
	global_load_dword v15, v16, s[8:9] sc1
	s_waitcnt lgkmcnt(0)
	global_load_dword v0, v16, s[10:11] sc1
	global_load_dword v1, v16, s[12:13] sc1
	global_load_dword v2, v16, s[16:17] sc1
	global_load_dword v3, v16, s[18:19] sc1
	global_load_dword v4, v16, s[20:21] sc1
	global_load_dword v5, v16, s[22:23] sc1
	global_load_dword v6, v16, s[24:25] sc1
	global_load_dword v7, v16, s[26:27] sc1
	global_load_dword v8, v16, s[28:29] sc1
	global_load_dword v9, v16, s[30:31] sc1
	global_load_dword v10, v16, s[34:35] sc1
	global_load_dword v11, v16, s[36:37] sc1
	global_load_dword v12, v16, s[38:39] sc1
	global_load_dword v13, v16, s[40:41] sc1
	global_load_dword v14, v16, s[42:43] sc1
	s_mov_b64 s[44:45], -1
	s_mov_b64 s[46:47], -1
	s_waitcnt vmcnt(14)
	v_add_u32_e32 v17, v0, v15
	s_waitcnt vmcnt(13)
	v_add_u32_e32 v17, v17, v1
	s_waitcnt vmcnt(12)
	v_add_u32_e32 v17, v17, v2
	s_waitcnt vmcnt(11)
	v_add_u32_e32 v17, v17, v3
	s_waitcnt vmcnt(10)
	v_add_u32_e32 v17, v17, v4
	s_waitcnt vmcnt(9)
	v_add_u32_e32 v17, v17, v5
	s_waitcnt vmcnt(8)
	v_add_u32_e32 v17, v17, v6
	s_waitcnt vmcnt(7)
	v_add_u32_e32 v17, v17, v7
	s_waitcnt vmcnt(6)
	v_add_u32_e32 v17, v17, v8
	s_waitcnt vmcnt(5)
	v_add_u32_e32 v17, v17, v9
	s_waitcnt vmcnt(4)
	v_add_u32_e32 v17, v17, v10
	s_waitcnt vmcnt(3)
	v_add_u32_e32 v17, v17, v11
	s_waitcnt vmcnt(2)
	v_add_u32_e32 v17, v17, v12
	s_waitcnt vmcnt(1)
	v_add_u32_e32 v17, v17, v13
	s_waitcnt vmcnt(0)
	v_add_u32_e32 v17, v17, v14
	v_cmp_eq_u32_e32 vcc, s0, v17
	s_cbranch_vccnz .LBB0_678
	s_and_b32 s2, s1, 0xff
	s_cmp_eq_u32 s2, 0
	s_mov_b64 s[48:49], -1
	s_sleep 14
	s_cbranch_scc0 .LBB0_683
	global_load_dword v17, v16, s[6:7] sc1
	s_waitcnt vmcnt(0)
	v_cmp_eq_u32_e32 vcc, 0, v17
	s_cbranch_vccnz .LBB0_685
	s_mov_b64 s[48:49], 0

; __device__ __forceinline__ unsigned xb_ld(unsigned* p)              { return __hip_atomic_load(p, __ATOMIC_RELAXED, __HIP_MEMORY_SCOPE_AGENT); }
; __device__ __forceinline__ unsigned xb_add(unsigned* p, unsigned v) { return __hip_atomic_fetch_add(p, v, __ATOMIC_RELAXED, __HIP_MEMORY_SCOPE_AGENT); }
; #define XB_SPIN(cond, bar) do { unsigned _sp = 0; while (cond) { __builtin_amdgcn_s_sleep(1); \
;     if ((++_sp & 255u) == 0u) { if (xb_ld(&(bar)[XB_TMO])) break; if (_sp > XB_SPIN_CAP) { atomicAdd(&(bar)[XB_TMO], 1u); break; } } } } while (0)
; __device__ __forceinline__ void xcd_barrier(const XcdBarrier& b) {
;     ...
;       else XB_SPIN(xb_ld(&bar[XB_TOPGEN]) == tg, bar);
;       __builtin_amdgcn_fence(__ATOMIC_ACQUIRE, "agent");
;       xb_add(&bar[XB_XGEN(b.x)], 1u);
;       asm volatile("s_waitcnt vmcnt(0)" ::: "memory");
;     } else {
;       XB_SPIN(xb_ld(&bar[XB_XGEN(b.x)]) == gen, bar);
.LBB0_697:
	s_and_b32 s1, s0, 0xff
	s_mov_b64 s[22:23], -1
	s_cmp_lg_u32 s1, 0
	s_mov_b64 s[26:27], -1
	s_sleep 14
	s_cbranch_scc1 .LBB0_700
	global_load_dword v2, v0, s[12:13] sc1
	s_waitcnt vmcnt(0)
	v_cmp_eq_u32_e32 vcc, 0, v2
	s_cbranch_vccnz .LBB0_702
	s_mov_b64 s[26:27], 0
	s_mov_b64 s[24:25], -1

; __device__ __forceinline__ unsigned xb_ld(unsigned* p)              { return __hip_atomic_load(p, __ATOMIC_RELAXED, __HIP_MEMORY_SCOPE_AGENT); }
; __device__ __forceinline__ unsigned xb_add(unsigned* p, unsigned v) { return __hip_atomic_fetch_add(p, v, __ATOMIC_RELAXED, __HIP_MEMORY_SCOPE_AGENT); }
; #define XB_SPIN(cond, bar) do { unsigned _sp = 0; while (cond) { __builtin_amdgcn_s_sleep(1); \
;     if ((++_sp & 255u) == 0u) { if (xb_ld(&(bar)[XB_TMO])) break; if (_sp > XB_SPIN_CAP) { atomicAdd(&(bar)[XB_TMO], 1u); break; } } } } while (0)
; __device__ __forceinline__ void xcd_barrier(const XcdBarrier& b) {
;     ...
;       else XB_SPIN(xb_ld(&bar[XB_TOPGEN]) == tg, bar);
;       __builtin_amdgcn_fence(__ATOMIC_ACQUIRE, "agent");
;       xb_add(&bar[XB_XGEN(b.x)], 1u);
;       asm volatile("s_waitcnt vmcnt(0)" ::: "memory");
;     } else {
;       XB_SPIN(xb_ld(&bar[XB_XGEN(b.x)]) == gen, bar);
.LBB0_714:
	s_and_b32 s1, s0, 0xff
	s_cmp_lg_u32 s1, 0
	s_mov_b64 s[24:25], -1
	s_sleep 14
	s_cbranch_scc1 .LBB0_717
	global_load_dword v1, v0, s[12:13] sc1
	s_waitcnt vmcnt(0)
	v_cmp_eq_u32_e32 vcc, 0, v1
	s_cbranch_vccnz .LBB0_719
	s_mov_b64 s[24:25], 0
	s_mov_b64 s[22:23], -1

; __device__ __forceinline__ unsigned xb_ld(unsigned* p)              { return __hip_atomic_load(p, __ATOMIC_RELAXED, __HIP_MEMORY_SCOPE_AGENT); }
; __device__ __forceinline__ void xcd_barrier_complete(unsigned* bar, unsigned x, unsigned& nloc, unsigned& nx) {
;     ...
;   for (;;) {
;     sum = 0u; cnt = 0u; mine = 0u;
; #pragma unroll
;     for (unsigned j = 0; j < 16; ++j) { const unsigned c = xb_ld(&bar[XB_XCNT(j)]); sum += c; cnt += (c > 0u) ? 1u : 0u; mine = (j == x) ? c : mine; }
;     if (sum == G) break;
;     __builtin_amdgcn_s_sleep(1);
;     if ((++sp & 255u) == 0u) { if (xb_ld(&bar[XB_TMO])) break; if (sp > XB_SPIN_CAP) { atomicAdd(&bar[XB_TMO], 1u); break; } }
;   }
.LBB0_775:
	global_load_dword v15, v16, s[16:17] sc1
	s_waitcnt lgkmcnt(0)
	global_load_dword v0, v16, s[18:19] sc1
	global_load_dword v1, v16, s[20:21] sc1
	global_load_dword v2, v16, s[22:23] sc1
	global_load_dword v3, v16, s[24:25] sc1
	global_load_dword v4, v16, s[26:27] sc1
	global_load_dword v5, v16, s[30:31] sc1
	global_load_dword v6, v16, s[34:35] sc1
	global_load_dword v7, v16, s[36:37] sc1
	global_load_dword v8, v16, s[38:39] sc1
	global_load_dword v9, v16, s[40:41] sc1
	global_load_dword v10, v16, s[42:43] sc1
	global_load_dword v11, v16, s[44:45] sc1
	global_load_dword v12, v16, s[46:47] sc1
	global_load_dword v13, v16, s[48:49] sc1
	global_load_dword v14, v16, s[50:51] sc1
	s_mov_b64 s[52:53], -1
	s_mov_b64 s[54:55], -1
	s_waitcnt vmcnt(14)
	v_add_u32_e32 v17, v0, v15
	s_waitcnt vmcnt(13)
	v_add_u32_e32 v17, v17, v1
	s_waitcnt vmcnt(12)
	v_add_u32_e32 v17, v17, v2
	s_waitcnt vmcnt(11)
	v_add_u32_e32 v17, v17, v3
	s_waitcnt vmcnt(10)
	v_add_u32_e32 v17, v17, v4
	s_waitcnt vmcnt(9)
	v_add_u32_e32 v17, v17, v5
	s_waitcnt vmcnt(8)
	v_add_u32_e32 v17, v17, v6
	s_waitcnt vmcnt(7)
	v_add_u32_e32 v17, v17, v7
	s_waitcnt vmcnt(6)
	v_add_u32_e32 v17, v17, v8
	s_waitcnt vmcnt(5)
	v_add_u32_e32 v17, v17, v9
	s_waitcnt vmcnt(4)
	v_add_u32_e32 v17, v17, v10
	s_waitcnt vmcnt(3)
	v_add_u32_e32 v17, v17, v11
	s_waitcnt vmcnt(2)
	v_add_u32_e32 v17, v17, v12
	s_waitcnt vmcnt(1)
	v_add_u32_e32 v17, v17, v13
	s_waitcnt vmcnt(0)
	v_add_u32_e32 v17, v17, v14
	v_cmp_eq_u32_e32 vcc, s0, v17
	s_cbranch_vccnz .LBB0_774
	s_and_b32 s2, s1, 0xff
	s_cmp_eq_u32 s2, 0
	s_mov_b64 s[56:57], -1
	s_sleep 14
	s_cbranch_scc0 .LBB0_779
	global_load_dword v17, v16, s[6:7] sc1
	s_waitcnt vmcnt(0)
	v_cmp_eq_u32_e32 vcc, 0, v17
	s_cbranch_vccnz .LBB0_781
	s_mov_b64 s[56:57], 0

; __device__ __forceinline__ unsigned xb_ld(unsigned* p)              { return __hip_atomic_load(p, __ATOMIC_RELAXED, __HIP_MEMORY_SCOPE_AGENT); }
; __device__ __forceinline__ unsigned xb_add(unsigned* p, unsigned v) { return __hip_atomic_fetch_add(p, v, __ATOMIC_RELAXED, __HIP_MEMORY_SCOPE_AGENT); }
; #define XB_SPIN(cond, bar) do { unsigned _sp = 0; while (cond) { __builtin_amdgcn_s_sleep(1); \
;     if ((++_sp & 255u) == 0u) { if (xb_ld(&(bar)[XB_TMO])) break; if (_sp > XB_SPIN_CAP) { atomicAdd(&(bar)[XB_TMO], 1u); break; } } } } while (0)
; __device__ __forceinline__ void xcd_barrier(const XcdBarrier& b) {
;     ...
;       else XB_SPIN(xb_ld(&bar[XB_TOPGEN]) == tg, bar);
;       __builtin_amdgcn_fence(__ATOMIC_ACQUIRE, "agent");
;       xb_add(&bar[XB_XGEN(b.x)], 1u);
;       asm volatile("s_waitcnt vmcnt(0)" ::: "memory");
;     } else {
;       XB_SPIN(xb_ld(&bar[XB_XGEN(b.x)]) == gen, bar);
.LBB0_793:
	s_and_b32 s1, s0, 0xff
	s_mov_b64 s[30:31], -1
	s_cmp_lg_u32 s1, 0
	s_mov_b64 s[36:37], -1
	s_sleep 14
	s_cbranch_scc1 .LBB0_796
	global_load_dword v2, v0, s[20:21] sc1
	s_waitcnt vmcnt(0)
	v_cmp_eq_u32_e32 vcc, 0, v2
	s_cbranch_vccnz .LBB0_798
	s_mov_b64 s[36:37], 0
	s_mov_b64 s[34:35], -1

; __device__ __forceinline__ unsigned xb_ld(unsigned* p)              { return __hip_atomic_load(p, __ATOMIC_RELAXED, __HIP_MEMORY_SCOPE_AGENT); }
; __device__ __forceinline__ unsigned xb_add(unsigned* p, unsigned v) { return __hip_atomic_fetch_add(p, v, __ATOMIC_RELAXED, __HIP_MEMORY_SCOPE_AGENT); }
; #define XB_SPIN(cond, bar) do { unsigned _sp = 0; while (cond) { __builtin_amdgcn_s_sleep(1); \
;     if ((++_sp & 255u) == 0u) { if (xb_ld(&(bar)[XB_TMO])) break; if (_sp > XB_SPIN_CAP) { atomicAdd(&(bar)[XB_TMO], 1u); break; } } } } while (0)
; __device__ __forceinline__ void xcd_barrier(const XcdBarrier& b) {
;     ...
;       else XB_SPIN(xb_ld(&bar[XB_TOPGEN]) == tg, bar);
;       __builtin_amdgcn_fence(__ATOMIC_ACQUIRE, "agent");
;       xb_add(&bar[XB_XGEN(b.x)], 1u);
;       asm volatile("s_waitcnt vmcnt(0)" ::: "memory");
;     } else {
;       XB_SPIN(xb_ld(&bar[XB_XGEN(b.x)]) == gen, bar);
.LBB0_810:
	s_and_b32 s1, s0, 0xff
	s_cmp_lg_u32 s1, 0
	s_mov_b64 s[34:35], -1
	s_sleep 14
	s_cbranch_scc1 .LBB0_813
	global_load_dword v1, v0, s[20:21] sc1
	s_waitcnt vmcnt(0)
	v_cmp_eq_u32_e32 vcc, 0, v1
	s_cbranch_vccnz .LBB0_815
	s_mov_b64 s[34:35], 0
	s_mov_b64 s[30:31], -1

; __device__ __forceinline__ unsigned xb_ld(unsigned* p)              { return __hip_atomic_load(p, __ATOMIC_RELAXED, __HIP_MEMORY_SCOPE_AGENT); }
; __device__ __forceinline__ void xcd_barrier_complete(unsigned* bar, unsigned x, unsigned& nloc, unsigned& nx) {
;     ...
;   for (;;) {
;     sum = 0u; cnt = 0u; mine = 0u;
; #pragma unroll
;     for (unsigned j = 0; j < 16; ++j) { const unsigned c = xb_ld(&bar[XB_XCNT(j)]); sum += c; cnt += (c > 0u) ? 1u : 0u; mine = (j == x) ? c : mine; }
;     if (sum == G) break;
;     __builtin_amdgcn_s_sleep(1);
;     if ((++sp & 255u) == 0u) { if (xb_ld(&bar[XB_TMO])) break; if (sp > XB_SPIN_CAP) { atomicAdd(&bar[XB_TMO], 1u); break; } }
;   }
.LBB0_1012:
	global_load_dword v15, v16, s[12:13] sc1
	s_waitcnt lgkmcnt(0)
	global_load_dword v0, v16, s[16:17] sc1
	global_load_dword v1, v16, s[18:19] sc1
	global_load_dword v2, v16, s[20:21] sc1
	global_load_dword v3, v16, s[22:23] sc1
	global_load_dword v4, v16, s[24:25] sc1
	global_load_dword v5, v16, s[26:27] sc1
	global_load_dword v6, v16, s[30:31] sc1
	global_load_dword v7, v16, s[34:35] sc1
	global_load_dword v8, v16, s[36:37] sc1
	global_load_dword v9, v16, s[38:39] sc1
	global_load_dword v10, v16, s[40:41] sc1
	global_load_dword v11, v16, s[42:43] sc1
	global_load_dword v12, v16, s[44:45] sc1
	global_load_dword v13, v16, s[46:47] sc1
	global_load_dword v14, v16, s[48:49] sc1
	s_mov_b64 s[50:51], -1
	s_mov_b64 s[52:53], -1
	s_waitcnt vmcnt(14)
	v_add_u32_e32 v17, v0, v15
	s_waitcnt vmcnt(13)
	v_add_u32_e32 v17, v17, v1
	s_waitcnt vmcnt(12)
	v_add_u32_e32 v17, v17, v2
	s_waitcnt vmcnt(11)
	v_add_u32_e32 v17, v17, v3
	s_waitcnt vmcnt(10)
	v_add_u32_e32 v17, v17, v4
	s_waitcnt vmcnt(9)
	v_add_u32_e32 v17, v17, v5
	s_waitcnt vmcnt(8)
	v_add_u32_e32 v17, v17, v6
	s_waitcnt vmcnt(7)
	v_add_u32_e32 v17, v17, v7
	s_waitcnt vmcnt(6)
	v_add_u32_e32 v17, v17, v8
	s_waitcnt vmcnt(5)
	v_add_u32_e32 v17, v17, v9
	s_waitcnt vmcnt(4)
	v_add_u32_e32 v17, v17, v10
	s_waitcnt vmcnt(3)
	v_add_u32_e32 v17, v17, v11
	s_waitcnt vmcnt(2)
	v_add_u32_e32 v17, v17, v12
	s_waitcnt vmcnt(1)
	v_add_u32_e32 v17, v17, v13
	s_waitcnt vmcnt(0)
	v_add_u32_e32 v17, v17, v14
	v_cmp_eq_u32_e32 vcc, s0, v17
	s_cbranch_vccnz .LBB0_1011
	s_and_b32 s2, s1, 0xff
	s_cmp_eq_u32 s2, 0
	s_mov_b64 s[54:55], -1
	s_sleep 14
	s_cbranch_scc0 .LBB0_1016
	global_load_dword v17, v16, s[8:9] sc1
	s_waitcnt vmcnt(0)
	v_cmp_eq_u32_e32 vcc, 0, v17
	s_cbranch_vccnz .LBB0_1018
	s_mov_b64 s[54:55], 0

; __device__ __forceinline__ unsigned xb_ld(unsigned* p)              { return __hip_atomic_load(p, __ATOMIC_RELAXED, __HIP_MEMORY_SCOPE_AGENT); }
; __device__ __forceinline__ unsigned xb_add(unsigned* p, unsigned v) { return __hip_atomic_fetch_add(p, v, __ATOMIC_RELAXED, __HIP_MEMORY_SCOPE_AGENT); }
; #define XB_SPIN(cond, bar) do { unsigned _sp = 0; while (cond) { __builtin_amdgcn_s_sleep(1); \
;     if ((++_sp & 255u) == 0u) { if (xb_ld(&(bar)[XB_TMO])) break; if (_sp > XB_SPIN_CAP) { atomicAdd(&(bar)[XB_TMO], 1u); break; } } } } while (0)
; __device__ __forceinline__ void xcd_barrier(const XcdBarrier& b) {
;     ...
;       else XB_SPIN(xb_ld(&bar[XB_TOPGEN]) == tg, bar);
;       __builtin_amdgcn_fence(__ATOMIC_ACQUIRE, "agent");
;       xb_add(&bar[XB_XGEN(b.x)], 1u);
;       asm volatile("s_waitcnt vmcnt(0)" ::: "memory");
;     } else {
;       XB_SPIN(xb_ld(&bar[XB_XGEN(b.x)]) == gen, bar);
.LBB0_1030:
	s_and_b32 s1, s0, 0xff
	s_mov_b64 s[26:27], -1
	s_cmp_lg_u32 s1, 0
	s_mov_b64 s[34:35], -1
	s_sleep 14
	s_cbranch_scc1 .LBB0_1033
	global_load_dword v2, v0, s[18:19] sc1
	s_waitcnt vmcnt(0)
	v_cmp_eq_u32_e32 vcc, 0, v2
	s_cbranch_vccnz .LBB0_1035
	s_mov_b64 s[34:35], 0
	s_mov_b64 s[30:31], -1

; __device__ __forceinline__ unsigned xb_ld(unsigned* p)              { return __hip_atomic_load(p, __ATOMIC_RELAXED, __HIP_MEMORY_SCOPE_AGENT); }
; __device__ __forceinline__ unsigned xb_add(unsigned* p, unsigned v) { return __hip_atomic_fetch_add(p, v, __ATOMIC_RELAXED, __HIP_MEMORY_SCOPE_AGENT); }
; #define XB_SPIN(cond, bar) do { unsigned _sp = 0; while (cond) { __builtin_amdgcn_s_sleep(1); \
;     if ((++_sp & 255u) == 0u) { if (xb_ld(&(bar)[XB_TMO])) break; if (_sp > XB_SPIN_CAP) { atomicAdd(&(bar)[XB_TMO], 1u); break; } } } } while (0)
; __device__ __forceinline__ void xcd_barrier(const XcdBarrier& b) {
;     ...
;       else XB_SPIN(xb_ld(&bar[XB_TOPGEN]) == tg, bar);
;       __builtin_amdgcn_fence(__ATOMIC_ACQUIRE, "agent");
;       xb_add(&bar[XB_XGEN(b.x)], 1u);
;       asm volatile("s_waitcnt vmcnt(0)" ::: "memory");
;     } else {
;       XB_SPIN(xb_ld(&bar[XB_XGEN(b.x)]) == gen, bar);
.LBB0_1047:
	s_and_b32 s1, s0, 0xff
	s_cmp_lg_u32 s1, 0
	s_mov_b64 s[30:31], -1
	s_sleep 14
	s_cbranch_scc1 .LBB0_1050
	global_load_dword v1, v0, s[18:19] sc1
	s_waitcnt vmcnt(0)
	v_cmp_eq_u32_e32 vcc, 0, v1
	s_cbranch_vccnz .LBB0_1052
	s_mov_b64 s[30:31], 0
	s_mov_b64 s[26:27], -1

; __device__ __forceinline__ unsigned xb_ld(unsigned* p)              { return __hip_atomic_load(p, __ATOMIC_RELAXED, __HIP_MEMORY_SCOPE_AGENT); }
; __device__ __forceinline__ void xcd_barrier_complete(unsigned* bar, unsigned x, unsigned& nloc, unsigned& nx) {
;     ...
;   for (;;) {
;     sum = 0u; cnt = 0u; mine = 0u;
; #pragma unroll
;     for (unsigned j = 0; j < 16; ++j) { const unsigned c = xb_ld(&bar[XB_XCNT(j)]); sum += c; cnt += (c > 0u) ? 1u : 0u; mine = (j == x) ? c : mine; }
;     if (sum == G) break;
;     __builtin_amdgcn_s_sleep(1);
;     if ((++sp & 255u) == 0u) { if (xb_ld(&bar[XB_TMO])) break; if (sp > XB_SPIN_CAP) { atomicAdd(&bar[XB_TMO], 1u); break; } }
;   }
.LBB0_1069:
	global_load_dword v15, v16, s[10:11] sc1
	s_waitcnt lgkmcnt(0)
	global_load_dword v0, v16, s[12:13] sc1
	global_load_dword v1, v16, s[16:17] sc1
	global_load_dword v2, v16, s[18:19] sc1
	global_load_dword v3, v16, s[20:21] sc1
	global_load_dword v4, v16, s[22:23] sc1
	global_load_dword v5, v16, s[24:25] sc1
	global_load_dword v6, v16, s[26:27] sc1
	global_load_dword v7, v16, s[30:31] sc1
	global_load_dword v8, v16, s[34:35] sc1
	global_load_dword v9, v16, s[36:37] sc1
	global_load_dword v10, v16, s[38:39] sc1
	global_load_dword v11, v16, s[40:41] sc1
	global_load_dword v12, v16, s[42:43] sc1
	global_load_dword v13, v16, s[44:45] sc1
	global_load_dword v14, v16, s[46:47] sc1
	s_mov_b64 s[48:49], -1
	s_mov_b64 s[50:51], -1
	s_waitcnt vmcnt(14)
	v_add_u32_e32 v17, v0, v15
	s_waitcnt vmcnt(13)
	v_add_u32_e32 v17, v17, v1
	s_waitcnt vmcnt(12)
	v_add_u32_e32 v17, v17, v2
	s_waitcnt vmcnt(11)
	v_add_u32_e32 v17, v17, v3
	s_waitcnt vmcnt(10)
	v_add_u32_e32 v17, v17, v4
	s_waitcnt vmcnt(9)
	v_add_u32_e32 v17, v17, v5
	s_waitcnt vmcnt(8)
	v_add_u32_e32 v17, v17, v6
	s_waitcnt vmcnt(7)
	v_add_u32_e32 v17, v17, v7
	s_waitcnt vmcnt(6)
	v_add_u32_e32 v17, v17, v8
	s_waitcnt vmcnt(5)
	v_add_u32_e32 v17, v17, v9
	s_waitcnt vmcnt(4)
	v_add_u32_e32 v17, v17, v10
	s_waitcnt vmcnt(3)
	v_add_u32_e32 v17, v17, v11
	s_waitcnt vmcnt(2)
	v_add_u32_e32 v17, v17, v12
	s_waitcnt vmcnt(1)
	v_add_u32_e32 v17, v17, v13
	s_waitcnt vmcnt(0)
	v_add_u32_e32 v17, v17, v14
	v_cmp_eq_u32_e32 vcc, s0, v17
	s_cbranch_vccnz .LBB0_1068
	s_and_b32 s2, s1, 0xff
	s_cmp_eq_u32 s2, 0
	s_mov_b64 s[52:53], -1
	s_sleep 14
	s_cbranch_scc0 .LBB0_1073
	global_load_dword v17, v16, s[8:9] sc1
	s_waitcnt vmcnt(0)
	v_cmp_eq_u32_e32 vcc, 0, v17
	s_cbranch_vccnz .LBB0_1075
	s_mov_b64 s[52:53], 0

; __device__ __forceinline__ unsigned xb_ld(unsigned* p)              { return __hip_atomic_load(p, __ATOMIC_RELAXED, __HIP_MEMORY_SCOPE_AGENT); }
; __device__ __forceinline__ unsigned xb_add(unsigned* p, unsigned v) { return __hip_atomic_fetch_add(p, v, __ATOMIC_RELAXED, __HIP_MEMORY_SCOPE_AGENT); }
; #define XB_SPIN(cond, bar) do { unsigned _sp = 0; while (cond) { __builtin_amdgcn_s_sleep(1); \
;     if ((++_sp & 255u) == 0u) { if (xb_ld(&(bar)[XB_TMO])) break; if (_sp > XB_SPIN_CAP) { atomicAdd(&(bar)[XB_TMO], 1u); break; } } } } while (0)
; __device__ __forceinline__ void xcd_barrier(const XcdBarrier& b) {
;     ...
;       else XB_SPIN(xb_ld(&bar[XB_TOPGEN]) == tg, bar);
;       __builtin_amdgcn_fence(__ATOMIC_ACQUIRE, "agent");
;       xb_add(&bar[XB_XGEN(b.x)], 1u);
;       asm volatile("s_waitcnt vmcnt(0)" ::: "memory");
;     } else {
;       XB_SPIN(xb_ld(&bar[XB_XGEN(b.x)]) == gen, bar);
.LBB0_1087:
	s_and_b32 s1, s0, 0xff
	s_mov_b64 s[24:25], -1
	s_cmp_lg_u32 s1, 0
	s_mov_b64 s[30:31], -1
	s_sleep 14
	s_cbranch_scc1 .LBB0_1090
	global_load_dword v2, v0, s[16:17] sc1
	s_waitcnt vmcnt(0)
	v_cmp_eq_u32_e32 vcc, 0, v2
	s_cbranch_vccnz .LBB0_1092
	s_mov_b64 s[30:31], 0
	s_mov_b64 s[26:27], -1

; __device__ __forceinline__ unsigned xb_ld(unsigned* p)              { return __hip_atomic_load(p, __ATOMIC_RELAXED, __HIP_MEMORY_SCOPE_AGENT); }
; __device__ __forceinline__ unsigned xb_add(unsigned* p, unsigned v) { return __hip_atomic_fetch_add(p, v, __ATOMIC_RELAXED, __HIP_MEMORY_SCOPE_AGENT); }
; #define XB_SPIN(cond, bar) do { unsigned _sp = 0; while (cond) { __builtin_amdgcn_s_sleep(1); \
;     if ((++_sp & 255u) == 0u) { if (xb_ld(&(bar)[XB_TMO])) break; if (_sp > XB_SPIN_CAP) { atomicAdd(&(bar)[XB_TMO], 1u); break; } } } } while (0)
; __device__ __forceinline__ void xcd_barrier(const XcdBarrier& b) {
;     ...
;       else XB_SPIN(xb_ld(&bar[XB_TOPGEN]) == tg, bar);
;       __builtin_amdgcn_fence(__ATOMIC_ACQUIRE, "agent");
;       xb_add(&bar[XB_XGEN(b.x)], 1u);
;       asm volatile("s_waitcnt vmcnt(0)" ::: "memory");
;     } else {
;       XB_SPIN(xb_ld(&bar[XB_XGEN(b.x)]) == gen, bar);
.LBB0_1104:
	s_and_b32 s1, s0, 0xff
	s_cmp_lg_u32 s1, 0
	s_mov_b64 s[26:27], -1
	s_sleep 14
	s_cbranch_scc1 .LBB0_1107
	global_load_dword v1, v0, s[16:17] sc1
	s_waitcnt vmcnt(0)
	v_cmp_eq_u32_e32 vcc, 0, v1
	s_cbranch_vccnz .LBB0_1109
	s_mov_b64 s[26:27], 0
	s_mov_b64 s[24:25], -1

; __device__ __forceinline__ unsigned xb_ld(unsigned* p)              { return __hip_atomic_load(p, __ATOMIC_RELAXED, __HIP_MEMORY_SCOPE_AGENT); }
; __device__ __forceinline__ void xcd_barrier_complete(unsigned* bar, unsigned x, unsigned& nloc, unsigned& nx) {
;     ...
;   for (;;) {
;     sum = 0u; cnt = 0u; mine = 0u;
; #pragma unroll
;     for (unsigned j = 0; j < 16; ++j) { const unsigned c = xb_ld(&bar[XB_XCNT(j)]); sum += c; cnt += (c > 0u) ? 1u : 0u; mine = (j == x) ? c : mine; }
;     if (sum == G) break;
;     __builtin_amdgcn_s_sleep(1);
;     if ((++sp & 255u) == 0u) { if (xb_ld(&bar[XB_TMO])) break; if (sp > XB_SPIN_CAP) { atomicAdd(&bar[XB_TMO], 1u); break; } }
;   }
.LBB0_1341:
	global_load_dword v15, v16, s[10:11] sc1
	s_waitcnt lgkmcnt(0)
	global_load_dword v0, v16, s[12:13] sc1
	global_load_dword v1, v16, s[14:15] sc1
	global_load_dword v2, v16, s[16:17] sc1
	global_load_dword v3, v16, s[18:19] sc1
	global_load_dword v4, v16, s[20:21] sc1
	global_load_dword v5, v16, s[22:23] sc1
	global_load_dword v6, v16, s[24:25] sc1
	global_load_dword v7, v16, s[26:27] sc1
	global_load_dword v8, v16, s[30:31] sc1
	global_load_dword v9, v16, s[34:35] sc1
	global_load_dword v10, v16, s[36:37] sc1
	global_load_dword v11, v16, s[38:39] sc1
	global_load_dword v12, v16, s[40:41] sc1
	global_load_dword v13, v16, s[42:43] sc1
	global_load_dword v14, v16, s[44:45] sc1
	s_mov_b64 s[46:47], -1
	s_mov_b64 s[48:49], -1
	s_waitcnt vmcnt(14)
	v_add_u32_e32 v17, v0, v15
	s_waitcnt vmcnt(13)
	v_add_u32_e32 v17, v17, v1
	s_waitcnt vmcnt(12)
	v_add_u32_e32 v17, v17, v2
	s_waitcnt vmcnt(11)
	v_add_u32_e32 v17, v17, v3
	s_waitcnt vmcnt(10)
	v_add_u32_e32 v17, v17, v4
	s_waitcnt vmcnt(9)
	v_add_u32_e32 v17, v17, v5
	s_waitcnt vmcnt(8)
	v_add_u32_e32 v17, v17, v6
	s_waitcnt vmcnt(7)
	v_add_u32_e32 v17, v17, v7
	s_waitcnt vmcnt(6)
	v_add_u32_e32 v17, v17, v8
	s_waitcnt vmcnt(5)
	v_add_u32_e32 v17, v17, v9
	s_waitcnt vmcnt(4)
	v_add_u32_e32 v17, v17, v10
	s_waitcnt vmcnt(3)
	v_add_u32_e32 v17, v17, v11
	s_waitcnt vmcnt(2)
	v_add_u32_e32 v17, v17, v12
	s_waitcnt vmcnt(1)
	v_add_u32_e32 v17, v17, v13
	s_waitcnt vmcnt(0)
	v_add_u32_e32 v17, v17, v14
	v_cmp_eq_u32_e32 vcc, s0, v17
	s_cbranch_vccnz .LBB0_1340
	s_and_b32 s2, s1, 0xff
	s_cmp_eq_u32 s2, 0
	s_mov_b64 s[50:51], -1
	s_sleep 14
	s_cbranch_scc0 .LBB0_1345
	global_load_dword v17, v16, s[8:9] sc1
	s_waitcnt vmcnt(0)
	v_cmp_eq_u32_e32 vcc, 0, v17
	s_cbranch_vccnz .LBB0_1347
	s_mov_b64 s[50:51], 0

; __device__ __forceinline__ unsigned xb_ld(unsigned* p)              { return __hip_atomic_load(p, __ATOMIC_RELAXED, __HIP_MEMORY_SCOPE_AGENT); }
; __device__ __forceinline__ unsigned xb_add(unsigned* p, unsigned v) { return __hip_atomic_fetch_add(p, v, __ATOMIC_RELAXED, __HIP_MEMORY_SCOPE_AGENT); }
; #define XB_SPIN(cond, bar) do { unsigned _sp = 0; while (cond) { __builtin_amdgcn_s_sleep(1); \
;     if ((++_sp & 255u) == 0u) { if (xb_ld(&(bar)[XB_TMO])) break; if (_sp > XB_SPIN_CAP) { atomicAdd(&(bar)[XB_TMO], 1u); break; } } } } while (0)
; __device__ __forceinline__ void xcd_barrier(const XcdBarrier& b) {
;     ...
;       else XB_SPIN(xb_ld(&bar[XB_TOPGEN]) == tg, bar);
;       __builtin_amdgcn_fence(__ATOMIC_ACQUIRE, "agent");
;       xb_add(&bar[XB_XGEN(b.x)], 1u);
;       asm volatile("s_waitcnt vmcnt(0)" ::: "memory");
;     } else {
;       XB_SPIN(xb_ld(&bar[XB_XGEN(b.x)]) == gen, bar);
.LBB0_1359:
	s_and_b32 s1, s0, 0xff
	s_mov_b64 s[22:23], -1
	s_cmp_lg_u32 s1, 0
	s_mov_b64 s[26:27], -1
	s_sleep 14
	s_cbranch_scc1 .LBB0_1362
	global_load_dword v2, v0, s[14:15] sc1
	s_waitcnt vmcnt(0)
	v_cmp_eq_u32_e32 vcc, 0, v2
	s_cbranch_vccnz .LBB0_1364
	s_mov_b64 s[26:27], 0
	s_mov_b64 s[24:25], -1

; __device__ __forceinline__ unsigned xb_ld(unsigned* p)              { return __hip_atomic_load(p, __ATOMIC_RELAXED, __HIP_MEMORY_SCOPE_AGENT); }
; __device__ __forceinline__ unsigned xb_add(unsigned* p, unsigned v) { return __hip_atomic_fetch_add(p, v, __ATOMIC_RELAXED, __HIP_MEMORY_SCOPE_AGENT); }
; #define XB_SPIN(cond, bar) do { unsigned _sp = 0; while (cond) { __builtin_amdgcn_s_sleep(1); \
;     if ((++_sp & 255u) == 0u) { if (xb_ld(&(bar)[XB_TMO])) break; if (_sp > XB_SPIN_CAP) { atomicAdd(&(bar)[XB_TMO], 1u); break; } } } } while (0)
; __device__ __forceinline__ void xcd_barrier(const XcdBarrier& b) {
;     ...
;       else XB_SPIN(xb_ld(&bar[XB_TOPGEN]) == tg, bar);
;       __builtin_amdgcn_fence(__ATOMIC_ACQUIRE, "agent");
;       xb_add(&bar[XB_XGEN(b.x)], 1u);
;       asm volatile("s_waitcnt vmcnt(0)" ::: "memory");
;     } else {
;       XB_SPIN(xb_ld(&bar[XB_XGEN(b.x)]) == gen, bar);
.LBB0_1376:
	s_and_b32 s1, s0, 0xff
	s_cmp_lg_u32 s1, 0
	s_mov_b64 s[24:25], -1
	s_sleep 14
	s_cbranch_scc1 .LBB0_1379
	global_load_dword v1, v0, s[14:15] sc1
	s_waitcnt vmcnt(0)
	v_cmp_eq_u32_e32 vcc, 0, v1
	s_cbranch_vccnz .LBB0_1381
	s_mov_b64 s[24:25], 0
	s_mov_b64 s[22:23], -1

; __device__ __forceinline__ unsigned xb_ld(unsigned* p)              { return __hip_atomic_load(p, __ATOMIC_RELAXED, __HIP_MEMORY_SCOPE_AGENT); }
; __device__ __forceinline__ void xcd_barrier_complete(unsigned* bar, unsigned x, unsigned& nloc, unsigned& nx) {
;     ...
;   for (;;) {
;     sum = 0u; cnt = 0u; mine = 0u;
; #pragma unroll
;     for (unsigned j = 0; j < 16; ++j) { const unsigned c = xb_ld(&bar[XB_XCNT(j)]); sum += c; cnt += (c > 0u) ? 1u : 0u; mine = (j == x) ? c : mine; }
;     if (sum == G) break;
;     __builtin_amdgcn_s_sleep(1);
;     if ((++sp & 255u) == 0u) { if (xb_ld(&bar[XB_TMO])) break; if (sp > XB_SPIN_CAP) { atomicAdd(&bar[XB_TMO], 1u); break; } }
;   }
.LBB0_1692:
	global_load_dword v15, v16, s[6:7] sc1
	s_waitcnt lgkmcnt(0)
	global_load_dword v0, v16, s[8:9] sc1
	global_load_dword v1, v16, s[10:11] sc1
	global_load_dword v2, v16, s[12:13] sc1
	global_load_dword v3, v16, s[14:15] sc1
	global_load_dword v4, v16, s[16:17] sc1
	global_load_dword v5, v16, s[18:19] sc1
	global_load_dword v6, v16, s[20:21] sc1
	global_load_dword v7, v16, s[22:23] sc1
	global_load_dword v8, v16, s[24:25] sc1
	global_load_dword v9, v16, s[26:27] sc1
	global_load_dword v10, v16, s[30:31] sc1
	global_load_dword v11, v16, s[34:35] sc1
	global_load_dword v12, v16, s[36:37] sc1
	global_load_dword v13, v16, s[38:39] sc1
	global_load_dword v14, v16, s[40:41] sc1
	s_mov_b64 s[42:43], -1
	s_mov_b64 s[44:45], -1
	s_waitcnt vmcnt(14)
	v_add_u32_e32 v17, v0, v15
	s_waitcnt vmcnt(13)
	v_add_u32_e32 v17, v17, v1
	s_waitcnt vmcnt(12)
	v_add_u32_e32 v17, v17, v2
	s_waitcnt vmcnt(11)
	v_add_u32_e32 v17, v17, v3
	s_waitcnt vmcnt(10)
	v_add_u32_e32 v17, v17, v4
	s_waitcnt vmcnt(9)
	v_add_u32_e32 v17, v17, v5
	s_waitcnt vmcnt(8)
	v_add_u32_e32 v17, v17, v6
	s_waitcnt vmcnt(7)
	v_add_u32_e32 v17, v17, v7
	s_waitcnt vmcnt(6)
	v_add_u32_e32 v17, v17, v8
	s_waitcnt vmcnt(5)
	v_add_u32_e32 v17, v17, v9
	s_waitcnt vmcnt(4)
	v_add_u32_e32 v17, v17, v10
	s_waitcnt vmcnt(3)
	v_add_u32_e32 v17, v17, v11
	s_waitcnt vmcnt(2)
	v_add_u32_e32 v17, v17, v12
	s_waitcnt vmcnt(1)
	v_add_u32_e32 v17, v17, v13
	s_waitcnt vmcnt(0)
	v_add_u32_e32 v17, v17, v14
	v_cmp_eq_u32_e32 vcc, s0, v17
	s_cbranch_vccnz .LBB0_1691
	s_and_b32 s33, s1, 0xff
	s_cmp_eq_u32 s33, 0
	s_mov_b64 s[46:47], -1
	s_sleep 14
	s_cbranch_scc0 .LBB0_1696
	global_load_dword v17, v16, s[4:5] sc1
	s_waitcnt vmcnt(0)
	v_cmp_eq_u32_e32 vcc, 0, v17
	s_cbranch_vccnz .LBB0_1698
	s_mov_b64 s[46:47], 0

; __device__ __forceinline__ unsigned xb_ld(unsigned* p)              { return __hip_atomic_load(p, __ATOMIC_RELAXED, __HIP_MEMORY_SCOPE_AGENT); }
; __device__ __forceinline__ unsigned xb_add(unsigned* p, unsigned v) { return __hip_atomic_fetch_add(p, v, __ATOMIC_RELAXED, __HIP_MEMORY_SCOPE_AGENT); }
; #define XB_SPIN(cond, bar) do { unsigned _sp = 0; while (cond) { __builtin_amdgcn_s_sleep(1); \
;     if ((++_sp & 255u) == 0u) { if (xb_ld(&(bar)[XB_TMO])) break; if (_sp > XB_SPIN_CAP) { atomicAdd(&(bar)[XB_TMO], 1u); break; } } } } while (0)
; __device__ __forceinline__ void xcd_barrier(const XcdBarrier& b) {
;     ...
;       else XB_SPIN(xb_ld(&bar[XB_TOPGEN]) == tg, bar);
;       __builtin_amdgcn_fence(__ATOMIC_ACQUIRE, "agent");
;       xb_add(&bar[XB_XGEN(b.x)], 1u);
;       asm volatile("s_waitcnt vmcnt(0)" ::: "memory");
;     } else {
;       XB_SPIN(xb_ld(&bar[XB_XGEN(b.x)]) == gen, bar);
.LBB0_1710:
	s_and_b32 s1, s0, 0xff
	s_mov_b64 s[18:19], -1
	s_cmp_lg_u32 s1, 0
	s_mov_b64 s[22:23], -1
	s_sleep 14
	s_cbranch_scc1 .LBB0_1713
	global_load_dword v2, v0, s[10:11] sc1
	s_waitcnt vmcnt(0)
	v_cmp_eq_u32_e32 vcc, 0, v2
	s_cbranch_vccnz .LBB0_1715
	s_mov_b64 s[22:23], 0
	s_mov_b64 s[20:21], -1

; __device__ __forceinline__ unsigned xb_ld(unsigned* p)              { return __hip_atomic_load(p, __ATOMIC_RELAXED, __HIP_MEMORY_SCOPE_AGENT); }
; __device__ __forceinline__ unsigned xb_add(unsigned* p, unsigned v) { return __hip_atomic_fetch_add(p, v, __ATOMIC_RELAXED, __HIP_MEMORY_SCOPE_AGENT); }
; #define XB_SPIN(cond, bar) do { unsigned _sp = 0; while (cond) { __builtin_amdgcn_s_sleep(1); \
;     if ((++_sp & 255u) == 0u) { if (xb_ld(&(bar)[XB_TMO])) break; if (_sp > XB_SPIN_CAP) { atomicAdd(&(bar)[XB_TMO], 1u); break; } } } } while (0)
; __device__ __forceinline__ void xcd_barrier(const XcdBarrier& b) {
;     ...
;       else XB_SPIN(xb_ld(&bar[XB_TOPGEN]) == tg, bar);
;       __builtin_amdgcn_fence(__ATOMIC_ACQUIRE, "agent");
;       xb_add(&bar[XB_XGEN(b.x)], 1u);
;       asm volatile("s_waitcnt vmcnt(0)" ::: "memory");
;     } else {
;       XB_SPIN(xb_ld(&bar[XB_XGEN(b.x)]) == gen, bar);
.LBB0_1727:
	s_and_b32 s1, s0, 0xff
	s_cmp_lg_u32 s1, 0
	s_mov_b64 s[20:21], -1
	s_sleep 14
	s_cbranch_scc1 .LBB0_1730
	global_load_dword v1, v0, s[10:11] sc1
	s_waitcnt vmcnt(0)
	v_cmp_eq_u32_e32 vcc, 0, v1
	s_cbranch_vccnz .LBB0_1732
	s_mov_b64 s[20:21], 0
	s_mov_b64 s[18:19], -1
